# m3_prompt chunk-total scan: all 32 loads of an 8-entry batch issued up front (was one dependent load pair per step)
# speedup vs baseline: 1.0152x; 1.0100x over previous
.LBB0_137:
	s_and_b64 vcc, exec, s[20:21]
	s_cbranch_vccz .LBB0_104
	s_ashr_i32 s20, s40, 31
	s_lshr_b32 s20, s20, 27
	s_add_i32 s21, s40, s20
	s_ashr_i32 s20, s21, 5
	s_andn2_b32 s21, s21, 31
	s_sub_i32 s41, s40, s21
	v_readfirstlane_b32 s42, v160
	s_waitcnt lgkmcnt(0)
	s_barrier
	s_and_saveexec_b64 s[24:25], s[52:53]
	s_movk_i32 s0, 0x1ff
	s_mov_b64 s[4:5], 0x8000
	s_cbranch_execz .LBB0_147
	s_cmp_gt_i32 s41, 0
	s_cselect_b64 s[26:27], -1, 0
	s_ashr_i32 s21, s20, 31
	s_lshl_b64 s[28:29], s[20:21], 15
	s_cmp_eq_u32 s41, 31
	s_cselect_b64 s[30:31], -1, 0
	s_or_b32 s34, s28, 0x7c00
	s_lshl_b64 s[36:37], s[20:21], 12
	v_readlane_b32 s3, v253, 21
	s_add_u32 s36, s3, s36
	v_readlane_b32 s3, v253, 22
	s_addc_u32 s37, s3, s37
	s_add_u32 s36, s36, 0x4080000
	s_addc_u32 s37, s37, 0
	s_lshl_b64 s[38:39], s[20:21], 17
	s_mov_b32 s35, s29
	v_lshl_add_u64 v[0:1], v[74:75], 0, s[38:39]
	s_lshl_b64 s[38:39], s[20:21], 17
	s_add_u32 s44, s78, s38
	s_addc_u32 s45, s79, s39
	s_add_u32 s38, s80, s38
	s_addc_u32 s39, s81, s39
	v_lshlrev_b32_e32 v2, 2, v160
	v_mov_b32_e32 v8, 0
	v_mov_b32_e32 v9, 0
	s_mov_b32 s21, 0
	s_cmp_lt_i32 s21, s41
	s_cbranch_scc0 .Lm3h_done
.Lm3h_loop:
	global_load_dword v212, v2, s[44:45]
	global_load_dword v213, v2, s[44:45] offset:2048
	global_load_dword v214, v2, s[38:39]
	global_load_dword v215, v2, s[38:39] offset:2048
	s_add_u32 s44, s44, 0x1000
	s_addc_u32 s45, s45, 0
	s_add_u32 s38, s38, 0x1000
	s_addc_u32 s39, s39, 0
	global_load_dword v216, v2, s[44:45]
	global_load_dword v217, v2, s[44:45] offset:2048
	global_load_dword v218, v2, s[38:39]
	global_load_dword v219, v2, s[38:39] offset:2048
	s_add_u32 s44, s44, 0x1000
	s_addc_u32 s45, s45, 0
	s_add_u32 s38, s38, 0x1000
	s_addc_u32 s39, s39, 0
	global_load_dword v220, v2, s[44:45]
	global_load_dword v221, v2, s[44:45] offset:2048
	global_load_dword v222, v2, s[38:39]
	global_load_dword v223, v2, s[38:39] offset:2048
	s_add_u32 s44, s44, 0x1000
	s_addc_u32 s45, s45, 0
	s_add_u32 s38, s38, 0x1000
	s_addc_u32 s39, s39, 0
	global_load_dword v224, v2, s[44:45]
	global_load_dword v225, v2, s[44:45] offset:2048
	global_load_dword v226, v2, s[38:39]
	global_load_dword v227, v2, s[38:39] offset:2048
	s_add_u32 s44, s44, 0x1000
	s_addc_u32 s45, s45, 0
	s_add_u32 s38, s38, 0x1000
	s_addc_u32 s39, s39, 0
	global_load_dword v228, v2, s[44:45]
	global_load_dword v229, v2, s[44:45] offset:2048
	global_load_dword v230, v2, s[38:39]
	global_load_dword v231, v2, s[38:39] offset:2048
	s_add_u32 s44, s44, 0x1000
	s_addc_u32 s45, s45, 0
	s_add_u32 s38, s38, 0x1000
	s_addc_u32 s39, s39, 0
	global_load_dword v232, v2, s[44:45]
	global_load_dword v233, v2, s[44:45] offset:2048
	global_load_dword v234, v2, s[38:39]
	global_load_dword v235, v2, s[38:39] offset:2048
	s_add_u32 s44, s44, 0x1000
	s_addc_u32 s45, s45, 0
	s_add_u32 s38, s38, 0x1000
	s_addc_u32 s39, s39, 0
	global_load_dword v236, v2, s[44:45]
	global_load_dword v237, v2, s[44:45] offset:2048
	global_load_dword v238, v2, s[38:39]
	global_load_dword v239, v2, s[38:39] offset:2048
	s_add_u32 s44, s44, 0x1000
	s_addc_u32 s45, s45, 0
	s_add_u32 s38, s38, 0x1000
	s_addc_u32 s39, s39, 0
	global_load_dword v242, v2, s[44:45]
	global_load_dword v243, v2, s[44:45] offset:2048
	global_load_dword v244, v2, s[38:39]
	global_load_dword v245, v2, s[38:39] offset:2048
	s_add_u32 s44, s44, 0x1000
	s_addc_u32 s45, s45, 0
	s_add_u32 s38, s38, 0x1000
	s_addc_u32 s39, s39, 0
	s_add_i32 s43, s21, 0
	s_cmp_lt_i32 s43, s41
	s_cselect_b64 vcc, -1, 0
	s_waitcnt vmcnt(28)
	s_nop 1
	v_cndmask_b32_e32 v212, 1.0, v212, vcc
	v_cndmask_b32_e32 v213, 1.0, v213, vcc
	v_cndmask_b32_e32 v214, 0, v214, vcc
	v_cndmask_b32_e32 v215, 0, v215, vcc
	v_fmac_f32_e32 v214, v8, v212
	v_fmac_f32_e32 v215, v9, v213
	s_add_i32 s43, s21, 1
	s_cmp_lt_i32 s43, s41
	s_cselect_b64 vcc, -1, 0
	s_waitcnt vmcnt(24)
	s_nop 1
	v_cndmask_b32_e32 v216, 1.0, v216, vcc
	v_cndmask_b32_e32 v217, 1.0, v217, vcc
	v_cndmask_b32_e32 v218, 0, v218, vcc
	v_cndmask_b32_e32 v219, 0, v219, vcc
	v_fmac_f32_e32 v218, v214, v216
	v_fmac_f32_e32 v219, v215, v217
	s_add_i32 s43, s21, 2
	s_cmp_lt_i32 s43, s41
	s_cselect_b64 vcc, -1, 0
	s_waitcnt vmcnt(20)
	s_nop 1
	v_cndmask_b32_e32 v220, 1.0, v220, vcc
	v_cndmask_b32_e32 v221, 1.0, v221, vcc
	v_cndmask_b32_e32 v222, 0, v222, vcc
	v_cndmask_b32_e32 v223, 0, v223, vcc
	v_fmac_f32_e32 v222, v218, v220
	v_fmac_f32_e32 v223, v219, v221
	s_add_i32 s43, s21, 3
	s_cmp_lt_i32 s43, s41
	s_cselect_b64 vcc, -1, 0
	s_waitcnt vmcnt(16)
	s_nop 1
	v_cndmask_b32_e32 v224, 1.0, v224, vcc
	v_cndmask_b32_e32 v225, 1.0, v225, vcc
	v_cndmask_b32_e32 v226, 0, v226, vcc
	v_cndmask_b32_e32 v227, 0, v227, vcc
	v_fmac_f32_e32 v226, v222, v224
	v_fmac_f32_e32 v227, v223, v225
	s_add_i32 s43, s21, 4
	s_cmp_lt_i32 s43, s41
	s_cselect_b64 vcc, -1, 0
	s_waitcnt vmcnt(12)
	s_nop 1
	v_cndmask_b32_e32 v228, 1.0, v228, vcc
	v_cndmask_b32_e32 v229, 1.0, v229, vcc
	v_cndmask_b32_e32 v230, 0, v230, vcc
	v_cndmask_b32_e32 v231, 0, v231, vcc
	v_fmac_f32_e32 v230, v226, v228
	v_fmac_f32_e32 v231, v227, v229
	s_add_i32 s43, s21, 5
	s_cmp_lt_i32 s43, s41
	s_cselect_b64 vcc, -1, 0
	s_waitcnt vmcnt(8)
	s_nop 1
	v_cndmask_b32_e32 v232, 1.0, v232, vcc
	v_cndmask_b32_e32 v233, 1.0, v233, vcc
	v_cndmask_b32_e32 v234, 0, v234, vcc
	v_cndmask_b32_e32 v235, 0, v235, vcc
	v_fmac_f32_e32 v234, v230, v232
	v_fmac_f32_e32 v235, v231, v233
	s_add_i32 s43, s21, 6
	s_cmp_lt_i32 s43, s41
	s_cselect_b64 vcc, -1, 0
	s_waitcnt vmcnt(4)
	s_nop 1
	v_cndmask_b32_e32 v236, 1.0, v236, vcc
	v_cndmask_b32_e32 v237, 1.0, v237, vcc
	v_cndmask_b32_e32 v238, 0, v238, vcc
	v_cndmask_b32_e32 v239, 0, v239, vcc
	v_fmac_f32_e32 v238, v234, v236
	v_fmac_f32_e32 v239, v235, v237
	s_add_i32 s43, s21, 7
	s_cmp_lt_i32 s43, s41
	s_cselect_b64 vcc, -1, 0
	s_waitcnt vmcnt(0)
	s_nop 1
	v_cndmask_b32_e32 v242, 1.0, v242, vcc
	v_cndmask_b32_e32 v243, 1.0, v243, vcc
	v_cndmask_b32_e32 v244, 0, v244, vcc
	v_cndmask_b32_e32 v245, 0, v245, vcc
	v_fmac_f32_e32 v244, v238, v242
	v_fmac_f32_e32 v245, v239, v243
	v_mov_b32_e32 v8, v244
	v_mov_b32_e32 v9, v245
	s_add_i32 s21, s21, 8
	s_cmp_lt_i32 s21, s41
	s_cbranch_scc1 .Lm3h_loop
.Lm3h_done:
	ds_write_b32 v2, v8
	ds_write_b32 v2, v9 offset:2048
	s_and_b64 vcc, exec, s[30:31]
	s_cbranch_vccz .LBB0_147
	s_sub_u32 s44, s44, 0x1000
	s_subb_u32 s45, s45, 0
	s_sub_u32 s38, s38, 0x1000
	s_subb_u32 s39, s39, 0
	global_load_dword v4, v2, s[44:45]
	global_load_dword v5, v2, s[44:45] offset:2048
	global_load_dword v6, v2, s[38:39]
	global_load_dword v7, v2, s[38:39] offset:2048
	s_waitcnt vmcnt(0)
	v_fmac_f32_e32 v6, v8, v4
	v_fmac_f32_e32 v7, v9, v5
	global_store_dword v2, v6, s[36:37]
	global_store_dword v2, v7, s[36:37] offset:2048
